# s27 with two early writebacks per XCD per barrier (1st and 17th arriving workgroup)
# baseline (speedup 1.0000x reference)
; __device__ __forceinline__ unsigned xb_ld(unsigned* p)              { return __hip_atomic_load(p, __ATOMIC_RELAXED, __HIP_MEMORY_SCOPE_AGENT); }
; __device__ __forceinline__ unsigned xb_add(unsigned* p, unsigned v) { return __hip_atomic_fetch_add(p, v, __ATOMIC_RELAXED, __HIP_MEMORY_SCOPE_AGENT); }
; #define XB_SPIN(cond, bar) do { unsigned _sp = 0; while (cond) { __builtin_amdgcn_s_sleep(1); \
;     if ((++_sp & 255u) == 0u) { if (xb_ld(&(bar)[XB_TMO])) break; if (_sp > XB_SPIN_CAP) { atomicAdd(&(bar)[XB_TMO], 1u); break; } } } } while (0)
; __device__ __forceinline__ void xcd_barrier(const XcdBarrier& b, const bool t0) {
;     ...
;         const unsigned old = xb_add(&bar[XB_XSUB(b.x)], 1u);
;         const unsigned gen = old / nloc;
;         if (old + 1u == (gen + 1u) * nloc) {
;             __builtin_amdgcn_fence(__ATOMIC_RELEASE, "agent");
;             asm volatile("s_waitcnt vmcnt(0)" ::: "memory");
;             const unsigned og = xb_add(&bar[XB_TOP], 1u);
;             const unsigned tg = og / nx;
;             if (og + 1u == (tg + 1u) * nx) xb_add(&bar[XB_TOPGEN], 1u);
;             else XB_SPIN(xb_ld(&bar[XB_TOPGEN]) == tg, bar);
;             __builtin_amdgcn_fence(__ATOMIC_ACQUIRE, "agent");
;             xb_add(&bar[XB_XGEN(b.x)], 1u);
;             asm volatile("s_waitcnt vmcnt(0)" ::: "memory");
;         } else {
;             XB_SPIN(xb_ld(&bar[XB_XGEN(b.x)]) == gen, bar);
.LBB0_56:
	s_or_b64 exec, exec, s[12:13]
	v_cvt_f32_u32_e32 v4, v2
	s_waitcnt vmcnt(0)
	v_readfirstlane_b32 s0, v3
	v_sub_u32_e32 v3, 0, v2
	v_rcp_iflag_f32_e32 v4, v4
	v_add_u32_e32 v5, s0, v1
	v_mul_f32_e32 v4, 0x4f7ffffe, v4
	v_cvt_u32_f32_e32 v4, v4
	v_mul_lo_u32 v1, v3, v4
	v_mul_hi_u32 v1, v4, v1
	v_add_u32_e32 v1, v4, v1
	v_mul_hi_u32 v1, v5, v1
	v_mul_lo_u32 v3, v1, v2
	v_sub_u32_e32 v3, v5, v3
	v_add_u32_e32 v4, 1, v1
	v_cmp_ge_u32_e32 vcc, v3, v2
	s_nop 1
	v_cndmask_b32_e32 v1, v1, v4, vcc
	v_sub_u32_e32 v4, v3, v2
	v_cndmask_b32_e32 v3, v3, v4, vcc
	v_add_u32_e32 v4, 1, v1
	v_cmp_ge_u32_e32 vcc, v3, v2
	v_add_u32_e32 v3, 1, v5
	s_nop 0
	v_cndmask_b32_e32 v1, v1, v4, vcc
	v_mul_lo_u32 v4, v2, v1
	v_add_u32_e32 v2, v4, v2
	v_cmp_ne_u32_e32 vcc, v3, v2
	s_and_saveexec_b64 s[0:1], vcc
	s_xor_b64 s[10:11], exec, s[0:1]
	s_cbranch_execz .LBB0_70
	v_sub_u32_e32 v0, v2, v3
	v_and_b32_e32 v0, 15, v0
	v_cmp_eq_u32_e32 vcc, 15, v0
	s_and_saveexec_b64 s[16:17], vcc
	s_cbranch_execz .Lfwb_8
	buffer_wbl2 sc1

; __device__ __forceinline__ unsigned xb_ld(unsigned* p)              { return __hip_atomic_load(p, __ATOMIC_RELAXED, __HIP_MEMORY_SCOPE_AGENT); }
; __device__ __forceinline__ unsigned xb_add(unsigned* p, unsigned v) { return __hip_atomic_fetch_add(p, v, __ATOMIC_RELAXED, __HIP_MEMORY_SCOPE_AGENT); }
; #define XB_SPIN(cond, bar) do { unsigned _sp = 0; while (cond) { __builtin_amdgcn_s_sleep(1); \
;     if ((++_sp & 255u) == 0u) { if (xb_ld(&(bar)[XB_TMO])) break; if (_sp > XB_SPIN_CAP) { atomicAdd(&(bar)[XB_TMO], 1u); break; } } } } while (0)
; __device__ __forceinline__ void xcd_barrier(const XcdBarrier& b, const bool t0) {
;     ...
;         const unsigned old = xb_add(&bar[XB_XSUB(b.x)], 1u);
;         const unsigned gen = old / nloc;
;         if (old + 1u == (gen + 1u) * nloc) {
;             __builtin_amdgcn_fence(__ATOMIC_RELEASE, "agent");
;             asm volatile("s_waitcnt vmcnt(0)" ::: "memory");
;             const unsigned og = xb_add(&bar[XB_TOP], 1u);
;             const unsigned tg = og / nx;
;             if (og + 1u == (tg + 1u) * nx) xb_add(&bar[XB_TOPGEN], 1u);
;             else XB_SPIN(xb_ld(&bar[XB_TOPGEN]) == tg, bar);
;             __builtin_amdgcn_fence(__ATOMIC_ACQUIRE, "agent");
;             xb_add(&bar[XB_XGEN(b.x)], 1u);
;             asm volatile("s_waitcnt vmcnt(0)" ::: "memory");
;         } else {
;             XB_SPIN(xb_ld(&bar[XB_XGEN(b.x)]) == gen, bar);
.LBB0_478:
	s_or_b64 exec, exec, s[12:13]
	v_cvt_f32_u32_e32 v4, v2
	s_waitcnt vmcnt(0)
	v_readfirstlane_b32 s0, v3
	v_sub_u32_e32 v3, 0, v2
	v_rcp_iflag_f32_e32 v4, v4
	v_add_u32_e32 v5, s0, v1
	v_mul_f32_e32 v4, 0x4f7ffffe, v4
	v_cvt_u32_f32_e32 v4, v4
	v_mul_lo_u32 v1, v3, v4
	v_mul_hi_u32 v1, v4, v1
	v_add_u32_e32 v1, v4, v1
	v_mul_hi_u32 v1, v5, v1
	v_mul_lo_u32 v3, v1, v2
	v_sub_u32_e32 v3, v5, v3
	v_add_u32_e32 v4, 1, v1
	v_cmp_ge_u32_e32 vcc, v3, v2
	s_nop 1
	v_cndmask_b32_e32 v1, v1, v4, vcc
	v_sub_u32_e32 v4, v3, v2
	v_cndmask_b32_e32 v3, v3, v4, vcc
	v_add_u32_e32 v4, 1, v1
	v_cmp_ge_u32_e32 vcc, v3, v2
	v_add_u32_e32 v3, 1, v5
	s_nop 0
	v_cndmask_b32_e32 v1, v1, v4, vcc
	v_mul_lo_u32 v4, v2, v1
	v_add_u32_e32 v2, v4, v2
	v_cmp_ne_u32_e32 vcc, v3, v2
	s_and_saveexec_b64 s[0:1], vcc
	s_xor_b64 s[10:11], exec, s[0:1]
	s_cbranch_execz .LBB0_492
	v_sub_u32_e32 v0, v2, v3
	v_and_b32_e32 v0, 15, v0
	v_cmp_eq_u32_e32 vcc, 15, v0
	s_and_saveexec_b64 s[22:23], vcc
	s_cbranch_execz .Lfwb_5
	buffer_wbl2 sc1

; __device__ __forceinline__ unsigned xb_ld(unsigned* p)              { return __hip_atomic_load(p, __ATOMIC_RELAXED, __HIP_MEMORY_SCOPE_AGENT); }
; __device__ __forceinline__ unsigned xb_add(unsigned* p, unsigned v) { return __hip_atomic_fetch_add(p, v, __ATOMIC_RELAXED, __HIP_MEMORY_SCOPE_AGENT); }
; #define XB_SPIN(cond, bar) do { unsigned _sp = 0; while (cond) { __builtin_amdgcn_s_sleep(1); \
;     if ((++_sp & 255u) == 0u) { if (xb_ld(&(bar)[XB_TMO])) break; if (_sp > XB_SPIN_CAP) { atomicAdd(&(bar)[XB_TMO], 1u); break; } } } } while (0)
; __device__ __forceinline__ void xcd_barrier(const XcdBarrier& b, const bool t0) {
;     ...
;         const unsigned old = xb_add(&bar[XB_XSUB(b.x)], 1u);
;         const unsigned gen = old / nloc;
;         if (old + 1u == (gen + 1u) * nloc) {
;             __builtin_amdgcn_fence(__ATOMIC_RELEASE, "agent");
;             asm volatile("s_waitcnt vmcnt(0)" ::: "memory");
;             const unsigned og = xb_add(&bar[XB_TOP], 1u);
;             const unsigned tg = og / nx;
;             if (og + 1u == (tg + 1u) * nx) xb_add(&bar[XB_TOPGEN], 1u);
;             else XB_SPIN(xb_ld(&bar[XB_TOPGEN]) == tg, bar);
;             __builtin_amdgcn_fence(__ATOMIC_ACQUIRE, "agent");
;             xb_add(&bar[XB_XGEN(b.x)], 1u);
;             asm volatile("s_waitcnt vmcnt(0)" ::: "memory");
;         } else {
;             XB_SPIN(xb_ld(&bar[XB_XGEN(b.x)]) == gen, bar);
.LBB0_558:
	s_or_b64 exec, exec, s[12:13]
	v_cvt_f32_u32_e32 v4, v2
	s_waitcnt vmcnt(0)
	v_readfirstlane_b32 s0, v3
	v_sub_u32_e32 v3, 0, v2
	v_rcp_iflag_f32_e32 v4, v4
	v_add_u32_e32 v5, s0, v1
	v_mul_f32_e32 v4, 0x4f7ffffe, v4
	v_cvt_u32_f32_e32 v4, v4
	v_mul_lo_u32 v1, v3, v4
	v_mul_hi_u32 v1, v4, v1
	v_add_u32_e32 v1, v4, v1
	v_mul_hi_u32 v1, v5, v1
	v_mul_lo_u32 v3, v1, v2
	v_sub_u32_e32 v3, v5, v3
	v_add_u32_e32 v4, 1, v1
	v_cmp_ge_u32_e32 vcc, v3, v2
	s_nop 1
	v_cndmask_b32_e32 v1, v1, v4, vcc
	v_sub_u32_e32 v4, v3, v2
	v_cndmask_b32_e32 v3, v3, v4, vcc
	v_add_u32_e32 v4, 1, v1
	v_cmp_ge_u32_e32 vcc, v3, v2
	v_add_u32_e32 v3, 1, v5
	s_nop 0
	v_cndmask_b32_e32 v1, v1, v4, vcc
	v_mul_lo_u32 v4, v2, v1
	v_add_u32_e32 v2, v4, v2
	v_cmp_ne_u32_e32 vcc, v3, v2
	s_and_saveexec_b64 s[0:1], vcc
	s_xor_b64 s[10:11], exec, s[0:1]
	s_cbranch_execz .LBB0_572
	v_sub_u32_e32 v0, v2, v3
	v_and_b32_e32 v0, 15, v0
	v_cmp_eq_u32_e32 vcc, 15, v0
	s_and_saveexec_b64 s[20:21], vcc
	s_cbranch_execz .Lfwb_4
	buffer_wbl2 sc1

; __device__ __forceinline__ unsigned xb_ld(unsigned* p)              { return __hip_atomic_load(p, __ATOMIC_RELAXED, __HIP_MEMORY_SCOPE_AGENT); }
; __device__ __forceinline__ unsigned xb_add(unsigned* p, unsigned v) { return __hip_atomic_fetch_add(p, v, __ATOMIC_RELAXED, __HIP_MEMORY_SCOPE_AGENT); }
; #define XB_SPIN(cond, bar) do { unsigned _sp = 0; while (cond) { __builtin_amdgcn_s_sleep(1); \
;     if ((++_sp & 255u) == 0u) { if (xb_ld(&(bar)[XB_TMO])) break; if (_sp > XB_SPIN_CAP) { atomicAdd(&(bar)[XB_TMO], 1u); break; } } } } while (0)
; __device__ __forceinline__ void xcd_barrier(const XcdBarrier& b, const bool t0) {
;     ...
;         const unsigned old = xb_add(&bar[XB_XSUB(b.x)], 1u);
;         const unsigned gen = old / nloc;
;         if (old + 1u == (gen + 1u) * nloc) {
;             __builtin_amdgcn_fence(__ATOMIC_RELEASE, "agent");
;             asm volatile("s_waitcnt vmcnt(0)" ::: "memory");
;             const unsigned og = xb_add(&bar[XB_TOP], 1u);
;             const unsigned tg = og / nx;
;             if (og + 1u == (tg + 1u) * nx) xb_add(&bar[XB_TOPGEN], 1u);
;             else XB_SPIN(xb_ld(&bar[XB_TOPGEN]) == tg, bar);
;             __builtin_amdgcn_fence(__ATOMIC_ACQUIRE, "agent");
;             xb_add(&bar[XB_XGEN(b.x)], 1u);
;             asm volatile("s_waitcnt vmcnt(0)" ::: "memory");
;         } else {
;             XB_SPIN(xb_ld(&bar[XB_XGEN(b.x)]) == gen, bar);
.LBB0_641:
	s_or_b64 exec, exec, s[12:13]
	v_cvt_f32_u32_e32 v4, v2
	s_waitcnt vmcnt(0)
	v_readfirstlane_b32 s0, v3
	v_sub_u32_e32 v3, 0, v2
	v_rcp_iflag_f32_e32 v4, v4
	v_add_u32_e32 v5, s0, v1
	v_mul_f32_e32 v4, 0x4f7ffffe, v4
	v_cvt_u32_f32_e32 v4, v4
	v_mul_lo_u32 v1, v3, v4
	v_mul_hi_u32 v1, v4, v1
	v_add_u32_e32 v1, v4, v1
	v_mul_hi_u32 v1, v5, v1
	v_mul_lo_u32 v3, v1, v2
	v_sub_u32_e32 v3, v5, v3
	v_add_u32_e32 v4, 1, v1
	v_cmp_ge_u32_e32 vcc, v3, v2
	s_nop 1
	v_cndmask_b32_e32 v1, v1, v4, vcc
	v_sub_u32_e32 v4, v3, v2
	v_cndmask_b32_e32 v3, v3, v4, vcc
	v_add_u32_e32 v4, 1, v1
	v_cmp_ge_u32_e32 vcc, v3, v2
	v_add_u32_e32 v3, 1, v5
	s_nop 0
	v_cndmask_b32_e32 v1, v1, v4, vcc
	v_mul_lo_u32 v4, v2, v1
	v_add_u32_e32 v2, v4, v2
	v_cmp_ne_u32_e32 vcc, v3, v2
	s_and_saveexec_b64 s[0:1], vcc
	s_xor_b64 s[10:11], exec, s[0:1]
	s_cbranch_execz .LBB0_655
	v_sub_u32_e32 v0, v2, v3
	v_and_b32_e32 v0, 15, v0
	v_cmp_eq_u32_e32 vcc, 15, v0
	s_and_saveexec_b64 s[18:19], vcc
	s_cbranch_execz .Lfwb_3
	buffer_wbl2 sc1
